# sgu phase: W-tile loads issued together, LN stats loads in two batches of 8 (were serialized); on top of K-split-11 and conversion rewrite
# speedup vs baseline: 1.0151x; 1.0034x over previous
.LBB0_267:
	s_ashr_i32 s36, s30, 4
	s_and_b32 s35, s30, 15
	s_lshl_b32 s34, s36, 7
	s_lshl_b32 s31, s35, 7
	v_add_u32_e32 v0, s34, v61
	v_or_b32_e32 v4, s31, v60
	v_ashrrev_i32_e32 v1, 31, v0
	v_lshlrev_b32_e32 v56, 2, v4
	v_lshlrev_b64 v[2:3], 13, v[0:1]
	v_lshlrev_b32_e32 v144, 1, v4
	v_or_b32_e32 v4, 4, v0
	v_lshl_add_u64 v[2:3], s[8:9], 0, v[2:3]
	v_ashrrev_i32_e32 v5, 31, v4
	v_lshl_add_u64 v[2:3], v[2:3], 0, v[144:145]
	v_lshlrev_b64 v[4:5], 13, v[4:5]
	v_add_co_u32_e32 v2, vcc, s53, v2
	v_lshl_add_u64 v[4:5], s[8:9], 0, v[4:5]
	s_nop 0
	v_addc_co_u32_e32 v3, vcc, 0, v3, vcc
	v_lshl_add_u64 v[4:5], v[4:5], 0, v[144:145]
	v_add_co_u32_e32 v4, vcc, s53, v4
	s_waitcnt lgkmcnt(0)
	global_load_dwordx4 v[16:19], v56, s[12:13] offset:16
	global_load_dwordx4 v[20:23], v56, s[14:15] offset:16
	global_load_dwordx4 v[24:27], v56, s[12:13]
	global_load_dwordx4 v[28:31], v56, s[14:15]
	v_addc_co_u32_e32 v5, vcc, 0, v5, vcc
	global_load_dwordx4 v[44:47], v[2:3], off
	global_load_dwordx4 v[40:43], v[4:5], off
	v_or_b32_e32 v2, 8, v0
	v_ashrrev_i32_e32 v3, 31, v2
	v_lshlrev_b64 v[2:3], 13, v[2:3]
	v_or_b32_e32 v0, 12, v0
	v_lshl_add_u64 v[2:3], s[8:9], 0, v[2:3]
	v_ashrrev_i32_e32 v1, 31, v0
	v_lshl_add_u64 v[2:3], v[2:3], 0, v[144:145]
	v_lshlrev_b64 v[0:1], 13, v[0:1]
	v_add_co_u32_e32 v2, vcc, s53, v2
	v_lshl_add_u64 v[0:1], s[8:9], 0, v[0:1]
	s_nop 0
	v_addc_co_u32_e32 v3, vcc, 0, v3, vcc
	v_lshl_add_u64 v[0:1], v[0:1], 0, v[144:145]
	v_add_u32_e32 v54, s34, v62
	v_add_co_u32_e32 v0, vcc, s53, v0
	v_or_b32_e32 v4, 16, v54
	s_nop 0
	v_addc_co_u32_e32 v1, vcc, 0, v1, vcc
	s_lshl_b32 s76, s35, 8
	v_ashrrev_i32_e32 v55, 31, v54
	v_ashrrev_i32_e32 v5, 31, v4
	global_load_dwordx4 v[36:39], v[2:3], off
	global_load_dwordx4 v[32:35], v[0:1], off
	v_lshl_add_u64 v[0:1], v[52:53], 0, s[76:77]
	v_lshlrev_b64 v[2:3], 13, v[54:55]
	v_lshlrev_b64 v[4:5], 13, v[4:5]
	v_lshl_add_u64 v[2:3], v[0:1], 0, v[2:3]
	v_lshl_add_u64 v[4:5], v[0:1], 0, v[4:5]
	global_load_dwordx4 v[12:15], v[2:3], off
	global_load_dwordx4 v[8:11], v[4:5], off
	v_or_b32_e32 v2, 32, v54
	v_or_b32_e32 v4, 48, v54
	v_ashrrev_i32_e32 v3, 31, v2
	v_ashrrev_i32_e32 v5, 31, v4
	v_lshlrev_b64 v[2:3], 13, v[2:3]
	v_lshlrev_b64 v[4:5], 13, v[4:5]
	v_lshl_add_u64 v[2:3], v[0:1], 0, v[2:3]
	v_lshl_add_u64 v[0:1], v[0:1], 0, v[4:5]
	global_load_dwordx4 v[4:7], v[2:3], off
	s_nop 0
	global_load_dwordx4 v[0:3], v[0:1], off
	s_barrier
	s_and_saveexec_b64 s[10:11], s[4:5]
	s_cbranch_execz .LBB0_269
	v_add_u32_e32 v48, s34, v58
	v_ashrrev_i32_e32 v49, 31, v48
	v_lshlrev_b64 v[48:49], 8, v[48:49]
	v_lshl_add_u64 v[48:49], s[24:25], 0, v[48:49]
	s_mov_b32 s6, 0x3a000000
	global_load_dwordx4 v[124:127], v[48:49], off
	global_load_dwordx4 v[128:131], v[48:49], off offset:16
	global_load_dwordx4 v[132:135], v[48:49], off offset:32
	global_load_dwordx4 v[136:139], v[48:49], off offset:48
	global_load_dwordx4 v[226:229], v[48:49], off offset:64
	global_load_dwordx4 v[230:233], v[48:49], off offset:80
	global_load_dwordx4 v[234:237], v[48:49], off offset:96
	global_load_dwordx4 v[238:241], v[48:49], off offset:112
	s_waitcnt vmcnt(7)
	v_add_f32_e32 v50, v124, v126
	v_add_f32_e32 v51, v125, v127
	s_waitcnt vmcnt(6)
	v_add_f32_e32 v57, v128, v130
	v_add_f32_e32 v50, v50, v57
	v_add_f32_e32 v57, v129, v131
	v_add_f32_e32 v51, v51, v57
	s_waitcnt vmcnt(5)
	v_add_f32_e32 v57, v132, v134
	v_add_f32_e32 v50, v50, v57
	v_add_f32_e32 v57, v133, v135
	v_add_f32_e32 v51, v51, v57
	s_waitcnt vmcnt(4)
	v_add_f32_e32 v57, v136, v138
	v_add_f32_e32 v50, v50, v57
	v_add_f32_e32 v57, v137, v139
	v_add_f32_e32 v51, v51, v57
	s_waitcnt vmcnt(3)
	v_add_f32_e32 v57, v226, v228
	v_add_f32_e32 v50, v50, v57
	v_add_f32_e32 v57, v227, v229
	v_add_f32_e32 v51, v51, v57
	s_waitcnt vmcnt(2)
	v_add_f32_e32 v57, v230, v232
	v_add_f32_e32 v50, v50, v57
	v_add_f32_e32 v57, v231, v233
	v_add_f32_e32 v51, v51, v57
	s_waitcnt vmcnt(1)
	v_add_f32_e32 v57, v234, v236
	v_add_f32_e32 v50, v50, v57
	v_add_f32_e32 v57, v235, v237
	v_add_f32_e32 v51, v51, v57
	s_waitcnt vmcnt(0)
	v_add_f32_e32 v57, v238, v240
	v_add_f32_e32 v50, v50, v57
	v_add_f32_e32 v57, v239, v241
	v_add_f32_e32 v51, v51, v57
	global_load_dwordx4 v[124:127], v[48:49], off offset:128
	global_load_dwordx4 v[128:131], v[48:49], off offset:144
	global_load_dwordx4 v[132:135], v[48:49], off offset:160
	global_load_dwordx4 v[136:139], v[48:49], off offset:176
	global_load_dwordx4 v[226:229], v[48:49], off offset:192
	global_load_dwordx4 v[230:233], v[48:49], off offset:208
	global_load_dwordx4 v[234:237], v[48:49], off offset:224
	global_load_dwordx4 v[238:241], v[48:49], off offset:240
	s_waitcnt vmcnt(7)
	v_add_f32_e32 v57, v124, v126
	v_add_f32_e32 v50, v50, v57
	v_add_f32_e32 v57, v125, v127
	v_add_f32_e32 v51, v51, v57
	s_waitcnt vmcnt(6)
	v_add_f32_e32 v57, v128, v130
	v_add_f32_e32 v50, v50, v57
	v_add_f32_e32 v57, v129, v131
	v_add_f32_e32 v51, v51, v57
	s_waitcnt vmcnt(5)
	v_add_f32_e32 v57, v132, v134
	v_add_f32_e32 v50, v50, v57
	v_add_f32_e32 v57, v133, v135
	v_add_f32_e32 v51, v51, v57
	s_waitcnt vmcnt(4)
	v_add_f32_e32 v57, v136, v138
	v_add_f32_e32 v50, v50, v57
	v_add_f32_e32 v57, v137, v139
	v_add_f32_e32 v51, v51, v57
	s_waitcnt vmcnt(3)
	v_add_f32_e32 v57, v226, v228
	v_add_f32_e32 v50, v50, v57
	v_add_f32_e32 v57, v227, v229
	v_add_f32_e32 v51, v51, v57
	s_waitcnt vmcnt(2)
	v_add_f32_e32 v57, v230, v232
	v_add_f32_e32 v50, v50, v57
	v_add_f32_e32 v57, v231, v233
	v_add_f32_e32 v51, v51, v57
	s_waitcnt vmcnt(1)
	v_add_f32_e32 v57, v234, v236
	v_add_f32_e32 v50, v50, v57
	v_add_f32_e32 v57, v235, v237
	v_add_f32_e32 v51, v51, v57
	s_waitcnt vmcnt(0)
	v_add_f32_e32 v57, v238, v240
	v_add_f32_e32 v50, v50, v57
	v_add_f32_e32 v57, v239, v241
	v_add_f32_e32 v51, v51, v57
	v_mul_f32_e32 v48, 0x3a000000, v50
	v_mov_b32_e32 v49, v51
	v_mul_f32_e32 v50, v48, v48
	v_fma_f32 v49, v49, s6, -v50
	v_max_f32_e32 v49, 0, v49
	v_add_f32_e32 v49, 0x358637bd, v49
	v_cmp_gt_f32_e32 vcc, s59, v49
	v_mul_f32_e32 v50, 0x4f800000, v49
	s_nop 0
	v_cndmask_b32_e32 v49, v49, v50, vcc
	v_sqrt_f32_e32 v50, v49
	s_nop 0
	v_add_u32_e32 v51, -1, v50
	v_fma_f32 v57, -v51, v50, v49
	v_cmp_ge_f32_e64 s[6:7], 0, v57
	v_add_u32_e32 v57, 1, v50
	s_nop 0
	v_cndmask_b32_e64 v51, v50, v51, s[6:7]
	v_fma_f32 v50, -v57, v50, v49
	v_cmp_lt_f32_e64 s[6:7], 0, v50
	s_nop 1
	v_cndmask_b32_e64 v50, v51, v57, s[6:7]
	v_mul_f32_e32 v51, 0x37800000, v50
	v_cndmask_b32_e32 v50, v50, v51, vcc
	v_cmp_class_f32_e32 vcc, v49, v187
	s_nop 1
	v_cndmask_b32_e32 v49, v50, v49, vcc
	v_div_scale_f32 v50, s[6:7], v49, v49, 1.0
	v_rcp_f32_e32 v51, v50
	s_nop 0
	v_fma_f32 v57, -v50, v51, 1.0
	v_fmac_f32_e32 v51, v57, v51
	v_div_scale_f32 v57, vcc, 1.0, v49, 1.0
	v_mul_f32_e32 v124, v57, v51
	v_fma_f32 v125, -v50, v124, v57
	v_fmac_f32_e32 v124, v125, v51
	v_fma_f32 v50, -v50, v124, v57
	v_div_fmas_f32 v50, v50, v51, v124
	v_div_fixup_f32 v49, v50, v49, 1.0
	ds_write_b64 v106, v[48:49]
.LBB0_269:
	s_or_b64 exec, exec, s[10:11]
	s_cmp_gt_i32 s36, 63
	s_cselect_b64 vcc, -1, 0
	s_lshl_b32 s6, s35, 16
	s_add_u32 s10, s16, s6
	s_addc_u32 s11, s17, 0
	v_cndmask_b32_e32 v48, v64, v66, vcc
	v_ashrrev_i32_e32 v49, 31, v48
	v_lshl_add_u64 v[48:49], v[48:49], 2, s[10:11]
	global_load_dwordx4 v[194:197], v[48:49], off
	v_cndmask_b32_e32 v48, v68, v70, vcc
	v_ashrrev_i32_e32 v49, 31, v48
	v_lshl_add_u64 v[48:49], v[48:49], 2, s[10:11]
	global_load_dwordx4 v[198:201], v[48:49], off
	v_cndmask_b32_e32 v48, v72, v74, vcc
	v_ashrrev_i32_e32 v49, 31, v48
	v_lshl_add_u64 v[48:49], v[48:49], 2, s[10:11]
	global_load_dwordx4 v[202:205], v[48:49], off
	v_cndmask_b32_e32 v48, v76, v78, vcc
	v_ashrrev_i32_e32 v49, 31, v48
	v_lshl_add_u64 v[48:49], v[48:49], 2, s[10:11]
	global_load_dwordx4 v[206:209], v[48:49], off
	v_cndmask_b32_e32 v48, v80, v82, vcc
	v_ashrrev_i32_e32 v49, 31, v48
	v_lshl_add_u64 v[48:49], v[48:49], 2, s[10:11]
	global_load_dwordx4 v[210:213], v[48:49], off
	v_cndmask_b32_e32 v48, v84, v86, vcc
	v_ashrrev_i32_e32 v49, 31, v48
	v_lshl_add_u64 v[48:49], v[48:49], 2, s[10:11]
	global_load_dwordx4 v[214:217], v[48:49], off
	v_cndmask_b32_e32 v48, v88, v90, vcc
	v_ashrrev_i32_e32 v49, 31, v48
	v_lshl_add_u64 v[48:49], v[48:49], 2, s[10:11]
	global_load_dwordx4 v[218:221], v[48:49], off
	v_cndmask_b32_e32 v48, v92, v94, vcc
	v_ashrrev_i32_e32 v49, 31, v48
	v_lshl_add_u64 v[48:49], v[48:49], 2, s[10:11]
	global_load_dwordx4 v[222:225], v[48:49], off
	s_add_i32 s35, s34, 0xffffe000
	s_cmp_lt_i32 s36, 64
	v_cndmask_b32_e32 v57, v65, v67, vcc
	s_waitcnt vmcnt(7)
	v_cmp_lt_i32_e64 s[6:7], -1, v57
	s_nop 1
	v_cndmask_b32_e64 v194, 0, v194, s[6:7]
	v_cmp_lt_i32_e64 s[6:7], 0, v57
	s_nop 1
	v_cndmask_b32_e64 v195, 0, v195, s[6:7]
	v_cmp_lt_i32_e64 s[6:7], 1, v57
	s_nop 1
	v_cndmask_b32_e64 v196, 0, v196, s[6:7]
	v_cmp_lt_i32_e64 s[6:7], 2, v57
	s_nop 1
	v_cndmask_b32_e64 v197, 0, v197, s[6:7]
	v_cvt_pk_bf16_f32 v194, v194, v195
	v_cvt_pk_bf16_f32 v195, v196, v197
	s_nop 0
	ds_write_b64 v107, v[194:195]
	v_cndmask_b32_e32 v57, v69, v71, vcc
	s_waitcnt vmcnt(6)
	v_cmp_lt_i32_e64 s[6:7], -1, v57
	s_nop 1
	v_cndmask_b32_e64 v198, 0, v198, s[6:7]
	v_cmp_lt_i32_e64 s[6:7], 0, v57
	s_nop 1
	v_cndmask_b32_e64 v199, 0, v199, s[6:7]
	v_cmp_lt_i32_e64 s[6:7], 1, v57
	s_nop 1
	v_cndmask_b32_e64 v200, 0, v200, s[6:7]
	v_cmp_lt_i32_e64 s[6:7], 2, v57
	s_nop 1
	v_cndmask_b32_e64 v201, 0, v201, s[6:7]
	v_cvt_pk_bf16_f32 v198, v198, v199
	v_cvt_pk_bf16_f32 v199, v200, v201
	s_nop 0
	ds_write_b64 v108, v[198:199]
	v_cndmask_b32_e32 v57, v73, v75, vcc
	s_waitcnt vmcnt(5)
	v_cmp_lt_i32_e64 s[6:7], -1, v57
	s_nop 1
	v_cndmask_b32_e64 v202, 0, v202, s[6:7]
	v_cmp_lt_i32_e64 s[6:7], 0, v57
	s_nop 1
	v_cndmask_b32_e64 v203, 0, v203, s[6:7]
	v_cmp_lt_i32_e64 s[6:7], 1, v57
	s_nop 1
	v_cndmask_b32_e64 v204, 0, v204, s[6:7]
	v_cmp_lt_i32_e64 s[6:7], 2, v57
	s_nop 1
	v_cndmask_b32_e64 v205, 0, v205, s[6:7]
	v_cvt_pk_bf16_f32 v202, v202, v203
	v_cvt_pk_bf16_f32 v203, v204, v205
	s_nop 0
	ds_write_b64 v109, v[202:203]
	v_cndmask_b32_e32 v57, v77, v79, vcc
	s_waitcnt vmcnt(4)
	v_cmp_lt_i32_e64 s[6:7], -1, v57
	s_nop 1
	v_cndmask_b32_e64 v206, 0, v206, s[6:7]
	v_cmp_lt_i32_e64 s[6:7], 0, v57
	s_nop 1
	v_cndmask_b32_e64 v207, 0, v207, s[6:7]
	v_cmp_lt_i32_e64 s[6:7], 1, v57
	s_nop 1
	v_cndmask_b32_e64 v208, 0, v208, s[6:7]
	v_cmp_lt_i32_e64 s[6:7], 2, v57
	s_nop 1
	v_cndmask_b32_e64 v209, 0, v209, s[6:7]
	v_cvt_pk_bf16_f32 v206, v206, v207
	v_cvt_pk_bf16_f32 v207, v208, v209
	s_nop 0
	ds_write_b64 v110, v[206:207]
	v_cndmask_b32_e32 v57, v81, v83, vcc
	s_waitcnt vmcnt(3)
	v_cmp_lt_i32_e64 s[6:7], -1, v57
	s_nop 1
	v_cndmask_b32_e64 v210, 0, v210, s[6:7]
	v_cmp_lt_i32_e64 s[6:7], 0, v57
	s_nop 1
	v_cndmask_b32_e64 v211, 0, v211, s[6:7]
	v_cmp_lt_i32_e64 s[6:7], 1, v57
	s_nop 1
	v_cndmask_b32_e64 v212, 0, v212, s[6:7]
	v_cmp_lt_i32_e64 s[6:7], 2, v57
	s_nop 1
	v_cndmask_b32_e64 v213, 0, v213, s[6:7]
	v_cvt_pk_bf16_f32 v210, v210, v211
	v_cvt_pk_bf16_f32 v211, v212, v213
	s_nop 0
	ds_write_b64 v111, v[210:211]
	v_cndmask_b32_e32 v57, v85, v87, vcc
	s_waitcnt vmcnt(2)
	v_cmp_lt_i32_e64 s[6:7], -1, v57
	s_nop 1
	v_cndmask_b32_e64 v214, 0, v214, s[6:7]
	v_cmp_lt_i32_e64 s[6:7], 0, v57
	s_nop 1
	v_cndmask_b32_e64 v215, 0, v215, s[6:7]
	v_cmp_lt_i32_e64 s[6:7], 1, v57
	s_nop 1
	v_cndmask_b32_e64 v216, 0, v216, s[6:7]
	v_cmp_lt_i32_e64 s[6:7], 2, v57
	s_nop 1
	v_cndmask_b32_e64 v217, 0, v217, s[6:7]
	v_cvt_pk_bf16_f32 v214, v214, v215
	v_cvt_pk_bf16_f32 v215, v216, v217
	s_nop 0
	ds_write_b64 v112, v[214:215]
	v_cndmask_b32_e32 v57, v89, v91, vcc
	s_waitcnt vmcnt(1)
	v_cmp_lt_i32_e64 s[6:7], -1, v57
	s_nop 1
	v_cndmask_b32_e64 v218, 0, v218, s[6:7]
	v_cmp_lt_i32_e64 s[6:7], 0, v57
	s_nop 1
	v_cndmask_b32_e64 v219, 0, v219, s[6:7]
	v_cmp_lt_i32_e64 s[6:7], 1, v57
	s_nop 1
	v_cndmask_b32_e64 v220, 0, v220, s[6:7]
	v_cmp_lt_i32_e64 s[6:7], 2, v57
	s_nop 1
	v_cndmask_b32_e64 v221, 0, v221, s[6:7]
	v_cvt_pk_bf16_f32 v218, v218, v219
	v_cvt_pk_bf16_f32 v219, v220, v221
	s_nop 0
	ds_write_b64 v113, v[218:219]
	v_cndmask_b32_e32 v57, v93, v95, vcc
	s_waitcnt vmcnt(0)
	v_cmp_lt_i32_e64 s[6:7], -1, v57
	s_nop 1
	v_cndmask_b32_e64 v222, 0, v222, s[6:7]
	v_cmp_lt_i32_e64 s[6:7], 0, v57
	s_nop 1
	v_cndmask_b32_e64 v223, 0, v223, s[6:7]
	v_cmp_lt_i32_e64 s[6:7], 1, v57
	s_nop 1
	v_cndmask_b32_e64 v224, 0, v224, s[6:7]
	v_cmp_lt_i32_e64 s[6:7], 2, v57
	s_nop 1
	v_cndmask_b32_e64 v225, 0, v225, s[6:7]
	v_cvt_pk_bf16_f32 v222, v222, v223
	v_cvt_pk_bf16_f32 v223, v224, v225
	s_nop 0
	ds_write_b64 v114, v[222:223]
	v_mov_b32_e32 v57, v145
	v_lshl_add_u64 v[56:57], s[28:29], 0, v[56:57]
	s_waitcnt lgkmcnt(0)
	s_barrier
	ds_read_b64 v[124:125], v115
	v_lshlrev_b32_e32 v48, 16, v44
	v_and_b32_e32 v49, 0xffff0000, v44
	v_lshlrev_b32_e32 v44, 16, v45
	v_and_b32_e32 v45, 0xffff0000, v45
	s_waitcnt lgkmcnt(0)
	v_pk_add_f32 v[44:45], v[44:45], v[124:125] op_sel_hi:[1,0] neg_lo:[0,1] neg_hi:[0,1]
	v_pk_add_f32 v[48:49], v[48:49], v[124:125] op_sel_hi:[1,0] neg_lo:[0,1] neg_hi:[0,1]
	v_pk_mul_f32 v[44:45], v[124:125], v[44:45] op_sel:[1,0]
	v_pk_mul_f32 v[48:49], v[124:125], v[48:49] op_sel:[1,0]
	v_pk_fma_f32 v[50:51], v[26:27], v[44:45], v[30:31]
	v_lshlrev_b32_e32 v44, 16, v46
	v_and_b32_e32 v45, 0xffff0000, v46
	v_lshlrev_b32_e32 v46, 16, v47
	v_and_b32_e32 v47, 0xffff0000, v47
	v_pk_add_f32 v[44:45], v[44:45], v[124:125] op_sel_hi:[1,0] neg_lo:[0,1] neg_hi:[0,1]
	v_pk_add_f32 v[46:47], v[46:47], v[124:125] op_sel_hi:[1,0] neg_lo:[0,1] neg_hi:[0,1]
	v_pk_mul_f32 v[44:45], v[124:125], v[44:45] op_sel:[1,0]
	v_pk_mul_f32 v[46:47], v[124:125], v[46:47] op_sel:[1,0]
	v_pk_fma_f32 v[48:49], v[24:25], v[48:49], v[28:29]
	v_pk_fma_f32 v[44:45], v[16:17], v[44:45], v[20:21]
	v_pk_fma_f32 v[46:47], v[18:19], v[46:47], v[22:23]
	s_cbranch_scc1 .LBB0_271
	v_add_u32_e32 v124, s35, v61
	v_ashrrev_i32_e32 v125, 31, v124
	v_lshlrev_b64 v[124:125], 13, v[124:125]
	v_lshl_add_u64 v[124:125], v[56:57], 0, v[124:125]
	global_store_dwordx4 v[124:125], v[48:51], off
	global_store_dwordx4 v[124:125], v[44:47], off offset:16
